# P4: hand-written weight-copy path (fp8 convert-then-transpose, 3 items in flight); copy workgroups join the scan ticket queue when done
# speedup vs baseline: 1.0051x; 1.0051x over previous
.Lscan_setup:
	s_add_u32 s0, s28, 0x14500000
	v_writelane_b32 v254, s0, 50
	s_addc_u32 s0, s29, 0
	v_writelane_b32 v254, s0, 51
	s_add_u32 s0, s28, 0x3800
	s_addc_u32 s1, s29, 0
	v_writelane_b32 v254, s0, 52
	s_cmpk_lt_i32 s2, 0x80
	v_lshrrev_b32_e32 v111, 4, v146
	v_writelane_b32 v254, s1, 53
	s_cselect_b64 s[0:1], -1, 0
	s_and_b64 s[70:71], s[0:1], s[38:39]
	s_cmp_lt_i32 s2, 64
	s_cselect_b64 s[24:25], -1, 0
	s_lshl_b32 s87, s20, 5
	s_add_i32 s0, s87, 0
	s_add_i32 s0, s0, 0x20000
	v_lshl_add_u32 v147, v111, 3, s0
	s_movk_i32 s0, 0x100
	v_cmp_gt_i32_e64 s[6:7], s0, v108
	s_lshl_b32 s0, s20, 2
	s_and_b32 s0, s0, 4
	v_and_b32_e32 v110, 15, v108
	s_lshl_b32 s92, s0, 4
	s_lshl_b32 s94, s0, 6
	s_or_b32 s1, s0, 1
	s_or_b32 s10, s0, 2
	s_or_b32 s0, s0, 3
	v_writelane_b32 v254, s20, 54
	s_lshl_b32 s95, s1, 6
	s_lshl_b32 s97, s0, 6
	s_lshl_b32 s3, s1, 4
	s_lshl_b32 s19, s0, 4
	v_cmp_eq_u32_e64 s[0:1], 0, v110
	s_lshl_b32 s52, s20, 4
	s_ashr_i32 s53, s52, 31
	v_writelane_b32 v254, s0, 55
	s_and_b32 s86, s2, 63
	s_add_i32 s90, 0, 0x1b000
	v_writelane_b32 v254, s1, 56
	v_writelane_b32 v254, s50, 57
	s_and_b32 s91, s52, 0xffffffe0
	s_or_b32 s93, s52, 16
	v_writelane_b32 v254, s51, 58
	s_lshl_b32 s96, s10, 6
	v_readlane_b32 s36, v254, 10
	s_lshl_b32 s18, s10, 4
	s_lshl_b64 s[16:17], s[52:53], 2
	v_readlane_b32 s46, v254, 20
	v_readlane_b32 s47, v254, 21
	s_add_u32 s0, s46, s16
	v_readlane_b32 s38, v254, 12
	s_addc_u32 s1, s47, s17
	v_readlane_b32 s39, v254, 13
	s_add_u32 s38, s28, 0xe500000
	v_readlane_b32 s40, v254, 14
	s_addc_u32 s39, s29, 0
	v_readlane_b32 s41, v254, 15
	s_add_u32 s40, s28, 0xe500800
	v_or_b32_e32 v0, 48, v146
	v_readlane_b32 s42, v254, 16
	s_addc_u32 s41, s29, 0
	v_mul_u32_u24_e32 v149, 0x120, v0
	v_lshlrev_b32_e32 v0, 4, v108
	v_and_b32_e32 v8, 1, v108
	v_readlane_b32 s43, v254, 17
	s_add_u32 s42, s28, 0xe500c00
	v_mov_b32_e32 v1, 0
	v_and_b32_e32 v12, 16, v0
	v_cmp_eq_u32_e32 vcc, 0, v8
	v_lshlrev_b32_e32 v13, 4, v8
	v_lshlrev_b32_e32 v8, 3, v108
	v_and_b32_e32 v165, 0xf0, v0
	v_and_b32_e32 v166, 0x70, v0
	v_readlane_b32 s37, v254, 11
	v_readlane_b32 s50, v254, 24
	v_readlane_b32 s51, v254, 25
	v_and_b32_e32 v0, 48, v146
	s_addc_u32 s43, s29, 0
	v_and_b32_e32 v163, 0x78, v8
	v_and_b32_e32 v164, 56, v8
	v_readlane_b32 s50, v254, 57
	v_readlane_b32 s36, v254, 44
	v_lshl_add_u64 v[8:9], s[0:1], 0, v[0:1]
	s_add_u32 s0, s28, 0x145c0000
	v_readlane_b32 s44, v254, 18
	v_readlane_b32 s45, v254, 19
	v_readlane_b32 s48, v254, 22
	v_readlane_b32 s49, v254, 23
	v_readlane_b32 s51, v254, 58
	v_readlane_b32 s37, v254, 45
	v_writelane_b32 v254, s0, 59
	s_addc_u32 s0, s29, 0
	v_writelane_b32 v254, s0, 60
	v_lshlrev_b32_e32 v10, 9, v110
	v_readlane_b32 s76, v254, 0
	v_readlane_b32 s80, v254, 4
	v_readlane_b32 s81, v254, 5
	v_readlane_b32 s82, v254, 6
	v_readlane_b32 s83, v254, 7
	s_mov_b64 s[12:13], s[80:81]
	s_mov_b64 s[14:15], s[82:83]
	s_add_u32 s0, s14, s16
	v_readlane_b32 s77, v254, 1
	v_readlane_b32 s78, v254, 2
	v_readlane_b32 s79, v254, 3
	v_writelane_b32 v254, s16, 61
	s_addc_u32 s1, s15, s17
	s_add_u32 s44, s28, 0x8500400
	v_mov_b32_e32 v11, v1
	s_addc_u32 s45, s29, 0
	v_lshl_add_u64 v[122:123], v[8:9], 0, v[10:11]
	v_lshl_add_u64 v[8:9], s[0:1], 0, v[0:1]
	s_add_u32 s48, s28, 0x10500000
	v_lshlrev_b32_e32 v2, 2, v111
	v_lshl_add_u64 v[8:9], v[8:9], 0, v[10:11]
	s_mov_b64 s[0:1], 0x5010200
	s_addc_u32 s49, s29, 0
	v_lshrrev_b32_e32 v3, 1, v108
	s_movk_i32 s89, 0xa0
	v_add_u32_e32 v5, 0x400, v108
	v_or_b32_e32 v162, s52, v2
	v_lshl_add_u64 v[124:125], v[8:9], 0, s[0:1]
	s_add_u32 s0, s28, 0x8500800
	v_mul_lo_u32 v3, v3, s89
	v_add_u32_e32 v4, 0x200, v108
	v_ashrrev_i32_e32 v154, 4, v5
	v_add_u32_e32 v5, 0x600, v108
	v_lshlrev_b32_e32 v114, 8, v162
	s_addc_u32 s1, s29, 0
	s_movk_i32 s85, 0x80
	v_add_u32_e32 v3, s90, v3
	v_ashrrev_i32_e32 v150, 4, v108
	v_ashrrev_i32_e32 v152, 4, v4
	v_ashrrev_i32_e32 v156, 4, v5
	v_ashrrev_i32_e32 v158, 3, v108
	v_ashrrev_i32_e32 v160, 3, v4
	v_mov_b32_e32 v109, v1
	v_or_b32_e32 v116, 0x100, v114
	v_or_b32_e32 v118, 0x200, v114
	v_or_b32_e32 v120, 0x300, v114
	v_mov_b32_e32 v4, 0x3f80
	s_add_u32 s65, s28, 0x14500bfc
	s_mov_b32 s21, 0
	v_cmp_eq_u32_e64 s[4:5], 0, v108
	s_movk_i32 s88, 0x120
	v_mul_u32_u24_e32 v148, 0x120, v110
	v_sub_u32_e32 v151, 0x7f, v150
	v_sub_u32_e32 v153, 0x7f, v152
	v_sub_u32_e32 v155, 0x7f, v154
	v_sub_u32_e32 v157, 0x7f, v156
	v_sub_u32_e32 v159, 0x7f, v158
	v_sub_u32_e32 v161, 0x7f, v160
	v_cmp_gt_i32_e64 s[8:9], s85, v108
	v_mov_b64_e32 v[112:113], v[108:109]
	v_ashrrev_i32_e32 v109, 31, v108
	v_cndmask_b32_e32 v4, 0, v4, vcc
	v_mov_b32_e32 v5, v1
	v_mov_b32_e32 v6, v1
	v_mov_b32_e32 v7, v1
	v_ashrrev_i32_e32 v115, 31, v114
	v_ashrrev_i32_e32 v117, 31, v116
	v_ashrrev_i32_e32 v119, 31, v118
	v_ashrrev_i32_e32 v121, 31, v120
	s_addc_u32 s84, s29, 0
	s_add_i32 s35, 0, 0x27fe0
	v_add_u32_e32 v167, v3, v12
	s_add_i32 s10, 0, 0x26600
	v_mov_b32_e32 v168, 0x145c0000
	v_add_u32_e32 v169, v3, v13
	s_movk_i32 s11, 0x1800
	v_mov_b32_e32 v170, 0x3db504f3
	v_lshlrev_b32_e32 v126, 2, v2
	v_mov_b32_e32 v171, 0x5010000
	v_mov_b32_e32 v186, v1
	v_mov_b32_e32 v187, v1
	v_mov_b32_e32 v188, v1
	v_mov_b32_e32 v189, v1
	v_mbcnt_hi_u32_b32 v172, -1, v185
	s_mov_b32 s68, 0
	s_mov_b32 s69, s2
	v_writelane_b32 v254, s17, 62
	s_branch .LBB0_577

.Lcp_entry:
	v_readfirstlane_b32 s0, v184
	v_and_b32_e32 v202, 63, v184
	s_lshr_b32 s0, s0, 6
	s_sub_u32 s1, s2, 208
	s_lshl_b32 s1, s1, 3
	s_add_u32 s3, s1, s0
	v_lshrrev_b32_e32 v200, 3, v202
	v_and_b32_e32 v201, 7, v202
	s_mul_i32 s4, s0, 4608
	v_mul_u32_u24_e32 v198, 0x240, v201
	v_lshl_add_u32 v198, v200, 2, v198
	v_add_u32_e32 v198, s4, v198
	v_mul_u32_u24_e32 v199, 0x90, v200
	v_lshl_add_u32 v199, v201, 4, v199
	v_add_u32_e32 v199, s4, v199
	v_lshlrev_b32_e32 v201, 4, v201
	s_mov_b32 s40, 0x43000000
	s_mov_b32 s41, 0x43000000
	v_readlane_b32 s10, v254, 38
	v_readlane_b32 s11, v254, 39
	v_readlane_b32 s12, v254, 2
	v_readlane_b32 s13, v254, 3
	v_readlane_b32 s98, v254, 4
	v_readlane_b32 s99, v254, 5
	s_mov_b32 s18, 0
	s_min_u32 s5, s3, 9215
	s_add_u32 s3, s3, 384
	s_cmp_lt_u32 s5, 0x400
	s_cbranch_scc1 .Lcp_m0_0
	s_cmp_lt_u32 s5, 0x1400
	s_cbranch_scc1 .Lcp_m1_0
	s_sub_u32 s5, s5, 0x1400
	s_and_b32 s1, s5, 63
	s_lshr_b32 s5, s5, 6
	s_mov_b32 s43, 13
	s_mov_b32 s55, 13
	s_mov_b64 s[6:7], s[98:99]
	s_add_u32 s8, s28, 0x4500000
	s_addc_u32 s9, s29, 0
	s_branch .Lcp_md_0
.Lcp_m0_0:
	s_and_b32 s1, s5, 63
	s_lshr_b32 s5, s5, 6
	s_mov_b32 s43, 13
	s_mov_b32 s55, 11
	s_mov_b64 s[6:7], s[10:11]
	s_add_u32 s8, s28, 0x1d00000
	s_addc_u32 s9, s29, 0
	s_branch .Lcp_md_0
.Lcp_m1_0:
	s_sub_u32 s5, s5, 0x400
	s_and_b32 s1, s5, 255
	s_lshr_b32 s5, s5, 8
	s_mov_b32 s43, 15
	s_mov_b32 s55, 11
	s_mov_b64 s[6:7], s[12:13]
	s_add_u32 s8, s28, 0x2500000
	s_addc_u32 s9, s29, 0
.Lcp_md_0:
	s_add_u32 s45, s43, 7
	s_lshl_b32 s53, s5, s45
	s_lshl_b32 s4, s1, 7
	s_add_u32 s53, s53, s4
	s_add_u32 s80, s6, s53
	s_addc_u32 s81, s7, 0
	s_add_u32 s45, s43, 5
	s_lshl_b32 s4, 1, s45
	s_add_u32 s82, s80, s4
	s_addc_u32 s83, s81, 0
	s_add_u32 s84, s82, s4
	s_addc_u32 s85, s83, 0
	s_add_u32 s86, s84, s4
	s_addc_u32 s87, s85, 0
	s_add_u32 s45, s55, 5
	s_lshl_b32 s4, s1, s45
	s_lshl_b32 s5, s5, 7
	s_add_u32 s4, s4, s5
	s_add_u32 s88, s8, s4
	s_addc_u32 s89, s9, 0
	s_add_u32 s45, s43, 2
	v_lshlrev_b32_e32 v194, s45, v200
	v_add_u32_e32 v194, v194, v201
	s_lshl_b32 s4, 1, s43
	v_add_u32_e32 v195, s4, v194
	v_add_u32_e32 v196, s4, v195
	v_add_u32_e32 v197, s4, v196
	global_load_dwordx4 v[0:3], v194, s[80:81]
	global_load_dwordx4 v[4:7], v195, s[80:81]
	global_load_dwordx4 v[8:11], v196, s[80:81]
	global_load_dwordx4 v[12:15], v197, s[80:81]
	global_load_dwordx4 v[16:19], v194, s[82:83]
	global_load_dwordx4 v[20:23], v195, s[82:83]
	global_load_dwordx4 v[24:27], v196, s[82:83]
	global_load_dwordx4 v[28:31], v197, s[82:83]
	global_load_dwordx4 v[32:35], v194, s[84:85]
	global_load_dwordx4 v[36:39], v195, s[84:85]
	global_load_dwordx4 v[40:43], v196, s[84:85]
	global_load_dwordx4 v[44:47], v197, s[84:85]
	global_load_dwordx4 v[48:51], v194, s[86:87]
	global_load_dwordx4 v[52:55], v195, s[86:87]
	global_load_dwordx4 v[56:59], v196, s[86:87]
	global_load_dwordx4 v[60:63], v197, s[86:87]
	s_min_u32 s5, s3, 9215
	s_add_u32 s3, s3, 384
	s_cmp_lt_u32 s5, 0x400
	s_cbranch_scc1 .Lcp_m0_1
	s_cmp_lt_u32 s5, 0x1400
	s_cbranch_scc1 .Lcp_m1_1
	s_sub_u32 s5, s5, 0x1400
	s_and_b32 s1, s5, 63
	s_lshr_b32 s5, s5, 6
	s_mov_b32 s43, 13
	s_mov_b32 s58, 13
	s_mov_b64 s[6:7], s[98:99]
	s_add_u32 s8, s28, 0x4500000
	s_addc_u32 s9, s29, 0
	s_branch .Lcp_md_1
.Lcp_m0_1:
	s_and_b32 s1, s5, 63
	s_lshr_b32 s5, s5, 6
	s_mov_b32 s43, 13
	s_mov_b32 s58, 11
	s_mov_b64 s[6:7], s[10:11]
	s_add_u32 s8, s28, 0x1d00000
	s_addc_u32 s9, s29, 0
	s_branch .Lcp_md_1
.Lcp_m1_1:
	s_sub_u32 s5, s5, 0x400
	s_and_b32 s1, s5, 255
	s_lshr_b32 s5, s5, 8
	s_mov_b32 s43, 15
	s_mov_b32 s58, 11
	s_mov_b64 s[6:7], s[12:13]
	s_add_u32 s8, s28, 0x2500000
	s_addc_u32 s9, s29, 0
.Lcp_md_1:
	s_add_u32 s45, s43, 7
	s_lshl_b32 s53, s5, s45
	s_lshl_b32 s4, s1, 7
	s_add_u32 s53, s53, s4
	s_add_u32 s80, s6, s53
	s_addc_u32 s81, s7, 0
	s_add_u32 s45, s43, 5
	s_lshl_b32 s4, 1, s45
	s_add_u32 s82, s80, s4
	s_addc_u32 s83, s81, 0
	s_add_u32 s84, s82, s4
	s_addc_u32 s85, s83, 0
	s_add_u32 s86, s84, s4
	s_addc_u32 s87, s85, 0
	s_add_u32 s45, s58, 5
	s_lshl_b32 s4, s1, s45
	s_lshl_b32 s5, s5, 7
	s_add_u32 s4, s4, s5
	s_add_u32 s90, s8, s4
	s_addc_u32 s91, s9, 0
	s_add_u32 s45, s43, 2
	v_lshlrev_b32_e32 v194, s45, v200
	v_add_u32_e32 v194, v194, v201
	s_lshl_b32 s4, 1, s43
	v_add_u32_e32 v195, s4, v194
	v_add_u32_e32 v196, s4, v195
	v_add_u32_e32 v197, s4, v196
	global_load_dwordx4 v[64:67], v194, s[80:81]
	global_load_dwordx4 v[68:71], v195, s[80:81]
	global_load_dwordx4 v[72:75], v196, s[80:81]
	global_load_dwordx4 v[76:79], v197, s[80:81]
	global_load_dwordx4 v[80:83], v194, s[82:83]
	global_load_dwordx4 v[84:87], v195, s[82:83]
	global_load_dwordx4 v[88:91], v196, s[82:83]
	global_load_dwordx4 v[92:95], v197, s[82:83]
	global_load_dwordx4 v[96:99], v194, s[84:85]
	global_load_dwordx4 v[100:103], v195, s[84:85]
	global_load_dwordx4 v[104:107], v196, s[84:85]
	global_load_dwordx4 v[108:111], v197, s[84:85]
	global_load_dwordx4 v[112:115], v194, s[86:87]
	global_load_dwordx4 v[116:119], v195, s[86:87]
	global_load_dwordx4 v[120:123], v196, s[86:87]
	global_load_dwordx4 v[124:127], v197, s[86:87]
	s_min_u32 s5, s3, 9215
	s_add_u32 s3, s3, 384
	s_cmp_lt_u32 s5, 0x400
	s_cbranch_scc1 .Lcp_m0_2
	s_cmp_lt_u32 s5, 0x1400
	s_cbranch_scc1 .Lcp_m1_2
	s_sub_u32 s5, s5, 0x1400
	s_and_b32 s1, s5, 63
	s_lshr_b32 s5, s5, 6
	s_mov_b32 s43, 13
	s_mov_b32 s59, 13
	s_mov_b64 s[6:7], s[98:99]
	s_add_u32 s8, s28, 0x4500000
	s_addc_u32 s9, s29, 0
	s_branch .Lcp_md_2
.Lcp_m0_2:
	s_and_b32 s1, s5, 63
	s_lshr_b32 s5, s5, 6
	s_mov_b32 s43, 13
	s_mov_b32 s59, 11
	s_mov_b64 s[6:7], s[10:11]
	s_add_u32 s8, s28, 0x1d00000
	s_addc_u32 s9, s29, 0
	s_branch .Lcp_md_2
.Lcp_m1_2:
	s_sub_u32 s5, s5, 0x400
	s_and_b32 s1, s5, 255
	s_lshr_b32 s5, s5, 8
	s_mov_b32 s43, 15
	s_mov_b32 s59, 11
	s_mov_b64 s[6:7], s[12:13]
	s_add_u32 s8, s28, 0x2500000
	s_addc_u32 s9, s29, 0
.Lcp_md_2:
	s_add_u32 s45, s43, 7
	s_lshl_b32 s53, s5, s45
	s_lshl_b32 s4, s1, 7
	s_add_u32 s53, s53, s4
	s_add_u32 s80, s6, s53
	s_addc_u32 s81, s7, 0
	s_add_u32 s45, s43, 5
	s_lshl_b32 s4, 1, s45
	s_add_u32 s82, s80, s4
	s_addc_u32 s83, s81, 0
	s_add_u32 s84, s82, s4
	s_addc_u32 s85, s83, 0
	s_add_u32 s86, s84, s4
	s_addc_u32 s87, s85, 0
	s_add_u32 s45, s59, 5
	s_lshl_b32 s4, s1, s45
	s_lshl_b32 s5, s5, 7
	s_add_u32 s4, s4, s5
	s_add_u32 s92, s8, s4
	s_addc_u32 s93, s9, 0
	s_add_u32 s45, s43, 2
	v_lshlrev_b32_e32 v194, s45, v200
	v_add_u32_e32 v194, v194, v201
	s_lshl_b32 s4, 1, s43
	v_add_u32_e32 v195, s4, v194
	v_add_u32_e32 v196, s4, v195
	v_add_u32_e32 v197, s4, v196
	global_load_dwordx4 v[128:131], v194, s[80:81]
	global_load_dwordx4 v[132:135], v195, s[80:81]
	global_load_dwordx4 v[136:139], v196, s[80:81]
	global_load_dwordx4 v[140:143], v197, s[80:81]
	global_load_dwordx4 v[144:147], v194, s[82:83]
	global_load_dwordx4 v[148:151], v195, s[82:83]
	global_load_dwordx4 v[152:155], v196, s[82:83]
	global_load_dwordx4 v[156:159], v197, s[82:83]
	global_load_dwordx4 v[160:163], v194, s[84:85]
	global_load_dwordx4 v[164:167], v195, s[84:85]
	global_load_dwordx4 v[168:171], v196, s[84:85]
	global_load_dwordx4 v[172:175], v197, s[84:85]
	global_load_dwordx4 v[176:179], v194, s[86:87]
	global_load_dwordx4 v[180:183], v195, s[86:87]
	global_load_dwordx4 v[186:189], v196, s[86:87]
	global_load_dwordx4 v[190:193], v197, s[86:87]
	s_waitcnt vmcnt(32)
	v_pk_mul_f32 v[0:1], v[0:1], s[40:41]
	v_pk_mul_f32 v[2:3], v[2:3], s[40:41]
	v_pk_mul_f32 v[4:5], v[4:5], s[40:41]
	v_pk_mul_f32 v[6:7], v[6:7], s[40:41]
	v_pk_mul_f32 v[8:9], v[8:9], s[40:41]
	v_pk_mul_f32 v[10:11], v[10:11], s[40:41]
	v_pk_mul_f32 v[12:13], v[12:13], s[40:41]
	v_pk_mul_f32 v[14:15], v[14:15], s[40:41]
	v_pk_mul_f32 v[16:17], v[16:17], s[40:41]
	v_pk_mul_f32 v[18:19], v[18:19], s[40:41]
	v_pk_mul_f32 v[20:21], v[20:21], s[40:41]
	v_pk_mul_f32 v[22:23], v[22:23], s[40:41]
	v_pk_mul_f32 v[24:25], v[24:25], s[40:41]
	v_pk_mul_f32 v[26:27], v[26:27], s[40:41]
	v_pk_mul_f32 v[28:29], v[28:29], s[40:41]
	v_pk_mul_f32 v[30:31], v[30:31], s[40:41]
	v_pk_mul_f32 v[32:33], v[32:33], s[40:41]
	v_pk_mul_f32 v[34:35], v[34:35], s[40:41]
	v_pk_mul_f32 v[36:37], v[36:37], s[40:41]
	v_pk_mul_f32 v[38:39], v[38:39], s[40:41]
	v_pk_mul_f32 v[40:41], v[40:41], s[40:41]
	v_pk_mul_f32 v[42:43], v[42:43], s[40:41]
	v_pk_mul_f32 v[44:45], v[44:45], s[40:41]
	v_pk_mul_f32 v[46:47], v[46:47], s[40:41]
	v_pk_mul_f32 v[48:49], v[48:49], s[40:41]
	v_pk_mul_f32 v[50:51], v[50:51], s[40:41]
	v_pk_mul_f32 v[52:53], v[52:53], s[40:41]
	v_pk_mul_f32 v[54:55], v[54:55], s[40:41]
	v_pk_mul_f32 v[56:57], v[56:57], s[40:41]
	v_pk_mul_f32 v[58:59], v[58:59], s[40:41]
	v_pk_mul_f32 v[60:61], v[60:61], s[40:41]
	v_pk_mul_f32 v[62:63], v[62:63], s[40:41]
	v_cvt_pk_fp8_f32 v0, v0, v4
	v_cvt_pk_fp8_f32 v1, v1, v5
	v_cvt_pk_fp8_f32 v2, v2, v6
	v_cvt_pk_fp8_f32 v3, v3, v7
	v_cvt_pk_fp8_f32 v0, v8, v12 op_sel:[0,0,1]
	v_cvt_pk_fp8_f32 v1, v9, v13 op_sel:[0,0,1]
	v_cvt_pk_fp8_f32 v2, v10, v14 op_sel:[0,0,1]
	v_cvt_pk_fp8_f32 v3, v11, v15 op_sel:[0,0,1]
	v_cvt_pk_fp8_f32 v16, v16, v20
	v_cvt_pk_fp8_f32 v17, v17, v21
	v_cvt_pk_fp8_f32 v18, v18, v22
	v_cvt_pk_fp8_f32 v19, v19, v23
	v_cvt_pk_fp8_f32 v16, v24, v28 op_sel:[0,0,1]
	v_cvt_pk_fp8_f32 v17, v25, v29 op_sel:[0,0,1]
	v_cvt_pk_fp8_f32 v18, v26, v30 op_sel:[0,0,1]
	v_cvt_pk_fp8_f32 v19, v27, v31 op_sel:[0,0,1]
	v_cvt_pk_fp8_f32 v32, v32, v36
	v_cvt_pk_fp8_f32 v33, v33, v37
	v_cvt_pk_fp8_f32 v34, v34, v38
	v_cvt_pk_fp8_f32 v35, v35, v39
	v_cvt_pk_fp8_f32 v32, v40, v44 op_sel:[0,0,1]
	v_cvt_pk_fp8_f32 v33, v41, v45 op_sel:[0,0,1]
	v_cvt_pk_fp8_f32 v34, v42, v46 op_sel:[0,0,1]
	v_cvt_pk_fp8_f32 v35, v43, v47 op_sel:[0,0,1]
	v_cvt_pk_fp8_f32 v48, v48, v52
	v_cvt_pk_fp8_f32 v49, v49, v53
	v_cvt_pk_fp8_f32 v50, v50, v54
	v_cvt_pk_fp8_f32 v51, v51, v55
	v_cvt_pk_fp8_f32 v48, v56, v60 op_sel:[0,0,1]
	v_cvt_pk_fp8_f32 v49, v57, v61 op_sel:[0,0,1]
	v_cvt_pk_fp8_f32 v50, v58, v62 op_sel:[0,0,1]
	v_cvt_pk_fp8_f32 v51, v59, v63 op_sel:[0,0,1]
	s_nop 0
	ds_write2_b32 v198, v0, v16 offset0:0 offset1:8
	ds_write2_b32 v198, v32, v48 offset0:16 offset1:24
	ds_write2_b32 v198, v1, v17 offset0:36 offset1:44
	ds_write2_b32 v198, v33, v49 offset0:52 offset1:60
	ds_write2_b32 v198, v2, v18 offset0:72 offset1:80
	ds_write2_b32 v198, v34, v50 offset0:88 offset1:96
	ds_write2_b32 v198, v3, v19 offset0:108 offset1:116
	ds_write2_b32 v198, v35, v51 offset0:124 offset1:132
	v_lshlrev_b32_e32 v8, s55, v200
	v_add_u32_e32 v8, v8, v201
	s_add_u32 s45, s55, 3
	s_lshl_b32 s4, 1, s45
	v_add_u32_e32 v24, s4, v8
	v_add_u32_e32 v40, s4, v24
	v_add_u32_e32 v56, s4, v40
	s_waitcnt lgkmcnt(0)
	ds_read_b128 v[4:7], v199 offset:0
	ds_read_b128 v[20:23], v199 offset:1152
	ds_read_b128 v[36:39], v199 offset:2304
	ds_read_b128 v[52:55], v199 offset:3456
	s_waitcnt lgkmcnt(3)
	global_store_dwordx4 v8, v[4:7], s[88:89]
	s_waitcnt lgkmcnt(2)
	global_store_dwordx4 v24, v[20:23], s[88:89]
	s_waitcnt lgkmcnt(1)
	global_store_dwordx4 v40, v[36:39], s[88:89]
	s_waitcnt lgkmcnt(0)
	global_store_dwordx4 v56, v[52:55], s[88:89]
	s_min_u32 s5, s3, 9215
	s_add_u32 s3, s3, 384
	s_cmp_lt_u32 s5, 0x400
	s_cbranch_scc1 .Lcp_m0_3
	s_cmp_lt_u32 s5, 0x1400
	s_cbranch_scc1 .Lcp_m1_3
	s_sub_u32 s5, s5, 0x1400
	s_and_b32 s1, s5, 63
	s_lshr_b32 s5, s5, 6
	s_mov_b32 s43, 13
	s_mov_b32 s55, 13
	s_mov_b64 s[6:7], s[98:99]
	s_add_u32 s8, s28, 0x4500000
	s_addc_u32 s9, s29, 0
	s_branch .Lcp_md_3

.Lcp_md_3:
	s_add_u32 s45, s43, 7
	s_lshl_b32 s53, s5, s45
	s_lshl_b32 s4, s1, 7
	s_add_u32 s53, s53, s4
	s_add_u32 s80, s6, s53
	s_addc_u32 s81, s7, 0
	s_add_u32 s45, s43, 5
	s_lshl_b32 s4, 1, s45
	s_add_u32 s82, s80, s4
	s_addc_u32 s83, s81, 0
	s_add_u32 s84, s82, s4
	s_addc_u32 s85, s83, 0
	s_add_u32 s86, s84, s4
	s_addc_u32 s87, s85, 0
	s_add_u32 s45, s55, 5
	s_lshl_b32 s4, s1, s45
	s_lshl_b32 s5, s5, 7
	s_add_u32 s4, s4, s5
	s_add_u32 s88, s8, s4
	s_addc_u32 s89, s9, 0
	s_add_u32 s45, s43, 2
	v_lshlrev_b32_e32 v194, s45, v200
	v_add_u32_e32 v194, v194, v201
	s_lshl_b32 s4, 1, s43
	v_add_u32_e32 v195, s4, v194
	v_add_u32_e32 v196, s4, v195
	v_add_u32_e32 v197, s4, v196
	global_load_dwordx4 v[0:3], v194, s[80:81]
	global_load_dwordx4 v[4:7], v195, s[80:81]
	global_load_dwordx4 v[8:11], v196, s[80:81]
	global_load_dwordx4 v[12:15], v197, s[80:81]
	global_load_dwordx4 v[16:19], v194, s[82:83]
	global_load_dwordx4 v[20:23], v195, s[82:83]
	global_load_dwordx4 v[24:27], v196, s[82:83]
	global_load_dwordx4 v[28:31], v197, s[82:83]
	global_load_dwordx4 v[32:35], v194, s[84:85]
	global_load_dwordx4 v[36:39], v195, s[84:85]
	global_load_dwordx4 v[40:43], v196, s[84:85]
	global_load_dwordx4 v[44:47], v197, s[84:85]
	global_load_dwordx4 v[48:51], v194, s[86:87]
	global_load_dwordx4 v[52:55], v195, s[86:87]
	global_load_dwordx4 v[56:59], v196, s[86:87]
	global_load_dwordx4 v[60:63], v197, s[86:87]
	s_waitcnt vmcnt(36)
	v_pk_mul_f32 v[64:65], v[64:65], s[40:41]
	v_pk_mul_f32 v[66:67], v[66:67], s[40:41]
	v_pk_mul_f32 v[68:69], v[68:69], s[40:41]
	v_pk_mul_f32 v[70:71], v[70:71], s[40:41]
	v_pk_mul_f32 v[72:73], v[72:73], s[40:41]
	v_pk_mul_f32 v[74:75], v[74:75], s[40:41]
	v_pk_mul_f32 v[76:77], v[76:77], s[40:41]
	v_pk_mul_f32 v[78:79], v[78:79], s[40:41]
	v_pk_mul_f32 v[80:81], v[80:81], s[40:41]
	v_pk_mul_f32 v[82:83], v[82:83], s[40:41]
	v_pk_mul_f32 v[84:85], v[84:85], s[40:41]
	v_pk_mul_f32 v[86:87], v[86:87], s[40:41]
	v_pk_mul_f32 v[88:89], v[88:89], s[40:41]
	v_pk_mul_f32 v[90:91], v[90:91], s[40:41]
	v_pk_mul_f32 v[92:93], v[92:93], s[40:41]
	v_pk_mul_f32 v[94:95], v[94:95], s[40:41]
	v_pk_mul_f32 v[96:97], v[96:97], s[40:41]
	v_pk_mul_f32 v[98:99], v[98:99], s[40:41]
	v_pk_mul_f32 v[100:101], v[100:101], s[40:41]
	v_pk_mul_f32 v[102:103], v[102:103], s[40:41]
	v_pk_mul_f32 v[104:105], v[104:105], s[40:41]
	v_pk_mul_f32 v[106:107], v[106:107], s[40:41]
	v_pk_mul_f32 v[108:109], v[108:109], s[40:41]
	v_pk_mul_f32 v[110:111], v[110:111], s[40:41]
	v_pk_mul_f32 v[112:113], v[112:113], s[40:41]
	v_pk_mul_f32 v[114:115], v[114:115], s[40:41]
	v_pk_mul_f32 v[116:117], v[116:117], s[40:41]
	v_pk_mul_f32 v[118:119], v[118:119], s[40:41]
	v_pk_mul_f32 v[120:121], v[120:121], s[40:41]
	v_pk_mul_f32 v[122:123], v[122:123], s[40:41]
	v_pk_mul_f32 v[124:125], v[124:125], s[40:41]
	v_pk_mul_f32 v[126:127], v[126:127], s[40:41]
	v_cvt_pk_fp8_f32 v64, v64, v68
	v_cvt_pk_fp8_f32 v65, v65, v69
	v_cvt_pk_fp8_f32 v66, v66, v70
	v_cvt_pk_fp8_f32 v67, v67, v71
	v_cvt_pk_fp8_f32 v64, v72, v76 op_sel:[0,0,1]
	v_cvt_pk_fp8_f32 v65, v73, v77 op_sel:[0,0,1]
	v_cvt_pk_fp8_f32 v66, v74, v78 op_sel:[0,0,1]
	v_cvt_pk_fp8_f32 v67, v75, v79 op_sel:[0,0,1]
	v_cvt_pk_fp8_f32 v80, v80, v84
	v_cvt_pk_fp8_f32 v81, v81, v85
	v_cvt_pk_fp8_f32 v82, v82, v86
	v_cvt_pk_fp8_f32 v83, v83, v87
	v_cvt_pk_fp8_f32 v80, v88, v92 op_sel:[0,0,1]
	v_cvt_pk_fp8_f32 v81, v89, v93 op_sel:[0,0,1]
	v_cvt_pk_fp8_f32 v82, v90, v94 op_sel:[0,0,1]
	v_cvt_pk_fp8_f32 v83, v91, v95 op_sel:[0,0,1]
	v_cvt_pk_fp8_f32 v96, v96, v100
	v_cvt_pk_fp8_f32 v97, v97, v101
	v_cvt_pk_fp8_f32 v98, v98, v102
	v_cvt_pk_fp8_f32 v99, v99, v103
	v_cvt_pk_fp8_f32 v96, v104, v108 op_sel:[0,0,1]
	v_cvt_pk_fp8_f32 v97, v105, v109 op_sel:[0,0,1]
	v_cvt_pk_fp8_f32 v98, v106, v110 op_sel:[0,0,1]
	v_cvt_pk_fp8_f32 v99, v107, v111 op_sel:[0,0,1]
	v_cvt_pk_fp8_f32 v112, v112, v116
	v_cvt_pk_fp8_f32 v113, v113, v117
	v_cvt_pk_fp8_f32 v114, v114, v118
	v_cvt_pk_fp8_f32 v115, v115, v119
	v_cvt_pk_fp8_f32 v112, v120, v124 op_sel:[0,0,1]
	v_cvt_pk_fp8_f32 v113, v121, v125 op_sel:[0,0,1]
	v_cvt_pk_fp8_f32 v114, v122, v126 op_sel:[0,0,1]
	v_cvt_pk_fp8_f32 v115, v123, v127 op_sel:[0,0,1]
	s_nop 0
	ds_write2_b32 v198, v64, v80 offset0:0 offset1:8
	ds_write2_b32 v198, v96, v112 offset0:16 offset1:24
	ds_write2_b32 v198, v65, v81 offset0:36 offset1:44
	ds_write2_b32 v198, v97, v113 offset0:52 offset1:60
	ds_write2_b32 v198, v66, v82 offset0:72 offset1:80
	ds_write2_b32 v198, v98, v114 offset0:88 offset1:96
	ds_write2_b32 v198, v67, v83 offset0:108 offset1:116
	ds_write2_b32 v198, v99, v115 offset0:124 offset1:132
	v_lshlrev_b32_e32 v72, s58, v200
	v_add_u32_e32 v72, v72, v201
	s_add_u32 s45, s58, 3
	s_lshl_b32 s4, 1, s45
	v_add_u32_e32 v88, s4, v72
	v_add_u32_e32 v104, s4, v88
	v_add_u32_e32 v120, s4, v104
	s_waitcnt lgkmcnt(0)
	ds_read_b128 v[68:71], v199 offset:0
	ds_read_b128 v[84:87], v199 offset:1152
	ds_read_b128 v[100:103], v199 offset:2304
	ds_read_b128 v[116:119], v199 offset:3456
	s_waitcnt lgkmcnt(3)
	global_store_dwordx4 v72, v[68:71], s[90:91]
	s_waitcnt lgkmcnt(2)
	global_store_dwordx4 v88, v[84:87], s[90:91]
	s_waitcnt lgkmcnt(1)
	global_store_dwordx4 v104, v[100:103], s[90:91]
	s_waitcnt lgkmcnt(0)
	global_store_dwordx4 v120, v[116:119], s[90:91]
	s_min_u32 s5, s3, 9215
	s_add_u32 s3, s3, 384
	s_cmp_lt_u32 s5, 0x400
	s_cbranch_scc1 .Lcp_m0_4
	s_cmp_lt_u32 s5, 0x1400
	s_cbranch_scc1 .Lcp_m1_4
	s_sub_u32 s5, s5, 0x1400
	s_and_b32 s1, s5, 63
	s_lshr_b32 s5, s5, 6
	s_mov_b32 s43, 13
	s_mov_b32 s58, 13
	s_mov_b64 s[6:7], s[98:99]
	s_add_u32 s8, s28, 0x4500000
	s_addc_u32 s9, s29, 0
	s_branch .Lcp_md_4

.Lcp_md_4:
	s_add_u32 s45, s43, 7
	s_lshl_b32 s53, s5, s45
	s_lshl_b32 s4, s1, 7
	s_add_u32 s53, s53, s4
	s_add_u32 s80, s6, s53
	s_addc_u32 s81, s7, 0
	s_add_u32 s45, s43, 5
	s_lshl_b32 s4, 1, s45
	s_add_u32 s82, s80, s4
	s_addc_u32 s83, s81, 0
	s_add_u32 s84, s82, s4
	s_addc_u32 s85, s83, 0
	s_add_u32 s86, s84, s4
	s_addc_u32 s87, s85, 0
	s_add_u32 s45, s58, 5
	s_lshl_b32 s4, s1, s45
	s_lshl_b32 s5, s5, 7
	s_add_u32 s4, s4, s5
	s_add_u32 s90, s8, s4
	s_addc_u32 s91, s9, 0
	s_add_u32 s45, s43, 2
	v_lshlrev_b32_e32 v194, s45, v200
	v_add_u32_e32 v194, v194, v201
	s_lshl_b32 s4, 1, s43
	v_add_u32_e32 v195, s4, v194
	v_add_u32_e32 v196, s4, v195
	v_add_u32_e32 v197, s4, v196
	global_load_dwordx4 v[64:67], v194, s[80:81]
	global_load_dwordx4 v[68:71], v195, s[80:81]
	global_load_dwordx4 v[72:75], v196, s[80:81]
	global_load_dwordx4 v[76:79], v197, s[80:81]
	global_load_dwordx4 v[80:83], v194, s[82:83]
	global_load_dwordx4 v[84:87], v195, s[82:83]
	global_load_dwordx4 v[88:91], v196, s[82:83]
	global_load_dwordx4 v[92:95], v197, s[82:83]
	global_load_dwordx4 v[96:99], v194, s[84:85]
	global_load_dwordx4 v[100:103], v195, s[84:85]
	global_load_dwordx4 v[104:107], v196, s[84:85]
	global_load_dwordx4 v[108:111], v197, s[84:85]
	global_load_dwordx4 v[112:115], v194, s[86:87]
	global_load_dwordx4 v[116:119], v195, s[86:87]
	global_load_dwordx4 v[120:123], v196, s[86:87]
	global_load_dwordx4 v[124:127], v197, s[86:87]
	s_waitcnt vmcnt(40)
	v_pk_mul_f32 v[128:129], v[128:129], s[40:41]
	v_pk_mul_f32 v[130:131], v[130:131], s[40:41]
	v_pk_mul_f32 v[132:133], v[132:133], s[40:41]
	v_pk_mul_f32 v[134:135], v[134:135], s[40:41]
	v_pk_mul_f32 v[136:137], v[136:137], s[40:41]
	v_pk_mul_f32 v[138:139], v[138:139], s[40:41]
	v_pk_mul_f32 v[140:141], v[140:141], s[40:41]
	v_pk_mul_f32 v[142:143], v[142:143], s[40:41]
	v_pk_mul_f32 v[144:145], v[144:145], s[40:41]
	v_pk_mul_f32 v[146:147], v[146:147], s[40:41]
	v_pk_mul_f32 v[148:149], v[148:149], s[40:41]
	v_pk_mul_f32 v[150:151], v[150:151], s[40:41]
	v_pk_mul_f32 v[152:153], v[152:153], s[40:41]
	v_pk_mul_f32 v[154:155], v[154:155], s[40:41]
	v_pk_mul_f32 v[156:157], v[156:157], s[40:41]
	v_pk_mul_f32 v[158:159], v[158:159], s[40:41]
	v_pk_mul_f32 v[160:161], v[160:161], s[40:41]
	v_pk_mul_f32 v[162:163], v[162:163], s[40:41]
	v_pk_mul_f32 v[164:165], v[164:165], s[40:41]
	v_pk_mul_f32 v[166:167], v[166:167], s[40:41]
	v_pk_mul_f32 v[168:169], v[168:169], s[40:41]
	v_pk_mul_f32 v[170:171], v[170:171], s[40:41]
	v_pk_mul_f32 v[172:173], v[172:173], s[40:41]
	v_pk_mul_f32 v[174:175], v[174:175], s[40:41]
	v_pk_mul_f32 v[176:177], v[176:177], s[40:41]
	v_pk_mul_f32 v[178:179], v[178:179], s[40:41]
	v_pk_mul_f32 v[180:181], v[180:181], s[40:41]
	v_pk_mul_f32 v[182:183], v[182:183], s[40:41]
	v_pk_mul_f32 v[186:187], v[186:187], s[40:41]
	v_pk_mul_f32 v[188:189], v[188:189], s[40:41]
	v_pk_mul_f32 v[190:191], v[190:191], s[40:41]
	v_pk_mul_f32 v[192:193], v[192:193], s[40:41]
	v_cvt_pk_fp8_f32 v128, v128, v132
	v_cvt_pk_fp8_f32 v129, v129, v133
	v_cvt_pk_fp8_f32 v130, v130, v134
	v_cvt_pk_fp8_f32 v131, v131, v135
	v_cvt_pk_fp8_f32 v128, v136, v140 op_sel:[0,0,1]
	v_cvt_pk_fp8_f32 v129, v137, v141 op_sel:[0,0,1]
	v_cvt_pk_fp8_f32 v130, v138, v142 op_sel:[0,0,1]
	v_cvt_pk_fp8_f32 v131, v139, v143 op_sel:[0,0,1]
	v_cvt_pk_fp8_f32 v144, v144, v148
	v_cvt_pk_fp8_f32 v145, v145, v149
	v_cvt_pk_fp8_f32 v146, v146, v150
	v_cvt_pk_fp8_f32 v147, v147, v151
	v_cvt_pk_fp8_f32 v144, v152, v156 op_sel:[0,0,1]
	v_cvt_pk_fp8_f32 v145, v153, v157 op_sel:[0,0,1]
	v_cvt_pk_fp8_f32 v146, v154, v158 op_sel:[0,0,1]
	v_cvt_pk_fp8_f32 v147, v155, v159 op_sel:[0,0,1]
	v_cvt_pk_fp8_f32 v160, v160, v164
	v_cvt_pk_fp8_f32 v161, v161, v165
	v_cvt_pk_fp8_f32 v162, v162, v166
	v_cvt_pk_fp8_f32 v163, v163, v167
	v_cvt_pk_fp8_f32 v160, v168, v172 op_sel:[0,0,1]
	v_cvt_pk_fp8_f32 v161, v169, v173 op_sel:[0,0,1]
	v_cvt_pk_fp8_f32 v162, v170, v174 op_sel:[0,0,1]
	v_cvt_pk_fp8_f32 v163, v171, v175 op_sel:[0,0,1]
	v_cvt_pk_fp8_f32 v176, v176, v180
	v_cvt_pk_fp8_f32 v177, v177, v181
	v_cvt_pk_fp8_f32 v178, v178, v182
	v_cvt_pk_fp8_f32 v179, v179, v183
	v_cvt_pk_fp8_f32 v176, v186, v190 op_sel:[0,0,1]
	v_cvt_pk_fp8_f32 v177, v187, v191 op_sel:[0,0,1]
	v_cvt_pk_fp8_f32 v178, v188, v192 op_sel:[0,0,1]
	v_cvt_pk_fp8_f32 v179, v189, v193 op_sel:[0,0,1]
	s_nop 0
	ds_write2_b32 v198, v128, v144 offset0:0 offset1:8
	ds_write2_b32 v198, v160, v176 offset0:16 offset1:24
	ds_write2_b32 v198, v129, v145 offset0:36 offset1:44
	ds_write2_b32 v198, v161, v177 offset0:52 offset1:60
	ds_write2_b32 v198, v130, v146 offset0:72 offset1:80
	ds_write2_b32 v198, v162, v178 offset0:88 offset1:96
	ds_write2_b32 v198, v131, v147 offset0:108 offset1:116
	ds_write2_b32 v198, v163, v179 offset0:124 offset1:132
	v_lshlrev_b32_e32 v136, s59, v200
	v_add_u32_e32 v136, v136, v201
	s_add_u32 s45, s59, 3
	s_lshl_b32 s4, 1, s45
	v_add_u32_e32 v152, s4, v136
	v_add_u32_e32 v168, s4, v152
	v_add_u32_e32 v186, s4, v168
	s_waitcnt lgkmcnt(0)
	ds_read_b128 v[132:135], v199 offset:0
	ds_read_b128 v[148:151], v199 offset:1152
	ds_read_b128 v[164:167], v199 offset:2304
	ds_read_b128 v[180:183], v199 offset:3456
	s_waitcnt lgkmcnt(3)
	global_store_dwordx4 v136, v[132:135], s[92:93]
	s_waitcnt lgkmcnt(2)
	global_store_dwordx4 v152, v[148:151], s[92:93]
	s_waitcnt lgkmcnt(1)
	global_store_dwordx4 v168, v[164:167], s[92:93]
	s_waitcnt lgkmcnt(0)
	global_store_dwordx4 v186, v[180:183], s[92:93]
	s_mov_b32 s18, 3
.Lcp_loop:
	s_min_u32 s5, s3, 9215
	s_add_u32 s3, s3, 384
	s_cmp_lt_u32 s5, 0x400
	s_cbranch_scc1 .Lcp_m0_5
	s_cmp_lt_u32 s5, 0x1400
	s_cbranch_scc1 .Lcp_m1_5
	s_sub_u32 s5, s5, 0x1400
	s_and_b32 s1, s5, 63
	s_lshr_b32 s5, s5, 6
	s_mov_b32 s43, 13
	s_mov_b32 s59, 13
	s_mov_b64 s[6:7], s[98:99]
	s_add_u32 s8, s28, 0x4500000
	s_addc_u32 s9, s29, 0
	s_branch .Lcp_md_5

.Lcp_md_5:
	s_add_u32 s45, s43, 7
	s_lshl_b32 s53, s5, s45
	s_lshl_b32 s4, s1, 7
	s_add_u32 s53, s53, s4
	s_add_u32 s80, s6, s53
	s_addc_u32 s81, s7, 0
	s_add_u32 s45, s43, 5
	s_lshl_b32 s4, 1, s45
	s_add_u32 s82, s80, s4
	s_addc_u32 s83, s81, 0
	s_add_u32 s84, s82, s4
	s_addc_u32 s85, s83, 0
	s_add_u32 s86, s84, s4
	s_addc_u32 s87, s85, 0
	s_add_u32 s45, s59, 5
	s_lshl_b32 s4, s1, s45
	s_lshl_b32 s5, s5, 7
	s_add_u32 s4, s4, s5
	s_add_u32 s92, s8, s4
	s_addc_u32 s93, s9, 0
	s_add_u32 s45, s43, 2
	v_lshlrev_b32_e32 v194, s45, v200
	v_add_u32_e32 v194, v194, v201
	s_lshl_b32 s4, 1, s43
	v_add_u32_e32 v195, s4, v194
	v_add_u32_e32 v196, s4, v195
	v_add_u32_e32 v197, s4, v196
	global_load_dwordx4 v[128:131], v194, s[80:81]
	global_load_dwordx4 v[132:135], v195, s[80:81]
	global_load_dwordx4 v[136:139], v196, s[80:81]
	global_load_dwordx4 v[140:143], v197, s[80:81]
	global_load_dwordx4 v[144:147], v194, s[82:83]
	global_load_dwordx4 v[148:151], v195, s[82:83]
	global_load_dwordx4 v[152:155], v196, s[82:83]
	global_load_dwordx4 v[156:159], v197, s[82:83]
	global_load_dwordx4 v[160:163], v194, s[84:85]
	global_load_dwordx4 v[164:167], v195, s[84:85]
	global_load_dwordx4 v[168:171], v196, s[84:85]
	global_load_dwordx4 v[172:175], v197, s[84:85]
	global_load_dwordx4 v[176:179], v194, s[86:87]
	global_load_dwordx4 v[180:183], v195, s[86:87]
	global_load_dwordx4 v[186:189], v196, s[86:87]
	global_load_dwordx4 v[190:193], v197, s[86:87]
	s_waitcnt vmcnt(40)
	v_pk_mul_f32 v[0:1], v[0:1], s[40:41]
	v_pk_mul_f32 v[2:3], v[2:3], s[40:41]
	v_pk_mul_f32 v[4:5], v[4:5], s[40:41]
	v_pk_mul_f32 v[6:7], v[6:7], s[40:41]
	v_pk_mul_f32 v[8:9], v[8:9], s[40:41]
	v_pk_mul_f32 v[10:11], v[10:11], s[40:41]
	v_pk_mul_f32 v[12:13], v[12:13], s[40:41]
	v_pk_mul_f32 v[14:15], v[14:15], s[40:41]
	v_pk_mul_f32 v[16:17], v[16:17], s[40:41]
	v_pk_mul_f32 v[18:19], v[18:19], s[40:41]
	v_pk_mul_f32 v[20:21], v[20:21], s[40:41]
	v_pk_mul_f32 v[22:23], v[22:23], s[40:41]
	v_pk_mul_f32 v[24:25], v[24:25], s[40:41]
	v_pk_mul_f32 v[26:27], v[26:27], s[40:41]
	v_pk_mul_f32 v[28:29], v[28:29], s[40:41]
	v_pk_mul_f32 v[30:31], v[30:31], s[40:41]
	v_pk_mul_f32 v[32:33], v[32:33], s[40:41]
	v_pk_mul_f32 v[34:35], v[34:35], s[40:41]
	v_pk_mul_f32 v[36:37], v[36:37], s[40:41]
	v_pk_mul_f32 v[38:39], v[38:39], s[40:41]
	v_pk_mul_f32 v[40:41], v[40:41], s[40:41]
	v_pk_mul_f32 v[42:43], v[42:43], s[40:41]
	v_pk_mul_f32 v[44:45], v[44:45], s[40:41]
	v_pk_mul_f32 v[46:47], v[46:47], s[40:41]
	v_pk_mul_f32 v[48:49], v[48:49], s[40:41]
	v_pk_mul_f32 v[50:51], v[50:51], s[40:41]
	v_pk_mul_f32 v[52:53], v[52:53], s[40:41]
	v_pk_mul_f32 v[54:55], v[54:55], s[40:41]
	v_pk_mul_f32 v[56:57], v[56:57], s[40:41]
	v_pk_mul_f32 v[58:59], v[58:59], s[40:41]
	v_pk_mul_f32 v[60:61], v[60:61], s[40:41]
	v_pk_mul_f32 v[62:63], v[62:63], s[40:41]
	v_cvt_pk_fp8_f32 v0, v0, v4
	v_cvt_pk_fp8_f32 v1, v1, v5
	v_cvt_pk_fp8_f32 v2, v2, v6
	v_cvt_pk_fp8_f32 v3, v3, v7
	v_cvt_pk_fp8_f32 v0, v8, v12 op_sel:[0,0,1]
	v_cvt_pk_fp8_f32 v1, v9, v13 op_sel:[0,0,1]
	v_cvt_pk_fp8_f32 v2, v10, v14 op_sel:[0,0,1]
	v_cvt_pk_fp8_f32 v3, v11, v15 op_sel:[0,0,1]
	v_cvt_pk_fp8_f32 v16, v16, v20
	v_cvt_pk_fp8_f32 v17, v17, v21
	v_cvt_pk_fp8_f32 v18, v18, v22
	v_cvt_pk_fp8_f32 v19, v19, v23
	v_cvt_pk_fp8_f32 v16, v24, v28 op_sel:[0,0,1]
	v_cvt_pk_fp8_f32 v17, v25, v29 op_sel:[0,0,1]
	v_cvt_pk_fp8_f32 v18, v26, v30 op_sel:[0,0,1]
	v_cvt_pk_fp8_f32 v19, v27, v31 op_sel:[0,0,1]
	v_cvt_pk_fp8_f32 v32, v32, v36
	v_cvt_pk_fp8_f32 v33, v33, v37
	v_cvt_pk_fp8_f32 v34, v34, v38
	v_cvt_pk_fp8_f32 v35, v35, v39
	v_cvt_pk_fp8_f32 v32, v40, v44 op_sel:[0,0,1]
	v_cvt_pk_fp8_f32 v33, v41, v45 op_sel:[0,0,1]
	v_cvt_pk_fp8_f32 v34, v42, v46 op_sel:[0,0,1]
	v_cvt_pk_fp8_f32 v35, v43, v47 op_sel:[0,0,1]
	v_cvt_pk_fp8_f32 v48, v48, v52
	v_cvt_pk_fp8_f32 v49, v49, v53
	v_cvt_pk_fp8_f32 v50, v50, v54
	v_cvt_pk_fp8_f32 v51, v51, v55
	v_cvt_pk_fp8_f32 v48, v56, v60 op_sel:[0,0,1]
	v_cvt_pk_fp8_f32 v49, v57, v61 op_sel:[0,0,1]
	v_cvt_pk_fp8_f32 v50, v58, v62 op_sel:[0,0,1]
	v_cvt_pk_fp8_f32 v51, v59, v63 op_sel:[0,0,1]
	s_nop 0
	ds_write2_b32 v198, v0, v16 offset0:0 offset1:8
	ds_write2_b32 v198, v32, v48 offset0:16 offset1:24
	ds_write2_b32 v198, v1, v17 offset0:36 offset1:44
	ds_write2_b32 v198, v33, v49 offset0:52 offset1:60
	ds_write2_b32 v198, v2, v18 offset0:72 offset1:80
	ds_write2_b32 v198, v34, v50 offset0:88 offset1:96
	ds_write2_b32 v198, v3, v19 offset0:108 offset1:116
	ds_write2_b32 v198, v35, v51 offset0:124 offset1:132
	v_lshlrev_b32_e32 v8, s55, v200
	v_add_u32_e32 v8, v8, v201
	s_add_u32 s45, s55, 3
	s_lshl_b32 s4, 1, s45
	v_add_u32_e32 v24, s4, v8
	v_add_u32_e32 v40, s4, v24
	v_add_u32_e32 v56, s4, v40
	s_waitcnt lgkmcnt(0)
	ds_read_b128 v[4:7], v199 offset:0
	ds_read_b128 v[20:23], v199 offset:1152
	ds_read_b128 v[36:39], v199 offset:2304
	ds_read_b128 v[52:55], v199 offset:3456
	s_waitcnt lgkmcnt(3)
	global_store_dwordx4 v8, v[4:7], s[88:89]
	s_waitcnt lgkmcnt(2)
	global_store_dwordx4 v24, v[20:23], s[88:89]
	s_waitcnt lgkmcnt(1)
	global_store_dwordx4 v40, v[36:39], s[88:89]
	s_waitcnt lgkmcnt(0)
	global_store_dwordx4 v56, v[52:55], s[88:89]
	s_min_u32 s5, s3, 9215
	s_add_u32 s3, s3, 384
	s_cmp_lt_u32 s5, 0x400
	s_cbranch_scc1 .Lcp_m0_6
	s_cmp_lt_u32 s5, 0x1400
	s_cbranch_scc1 .Lcp_m1_6
	s_sub_u32 s5, s5, 0x1400
	s_and_b32 s1, s5, 63
	s_lshr_b32 s5, s5, 6
	s_mov_b32 s43, 13
	s_mov_b32 s55, 13
	s_mov_b64 s[6:7], s[98:99]
	s_add_u32 s8, s28, 0x4500000
	s_addc_u32 s9, s29, 0
	s_branch .Lcp_md_6

.Lcp_md_6:
	s_add_u32 s45, s43, 7
	s_lshl_b32 s53, s5, s45
	s_lshl_b32 s4, s1, 7
	s_add_u32 s53, s53, s4
	s_add_u32 s80, s6, s53
	s_addc_u32 s81, s7, 0
	s_add_u32 s45, s43, 5
	s_lshl_b32 s4, 1, s45
	s_add_u32 s82, s80, s4
	s_addc_u32 s83, s81, 0
	s_add_u32 s84, s82, s4
	s_addc_u32 s85, s83, 0
	s_add_u32 s86, s84, s4
	s_addc_u32 s87, s85, 0
	s_add_u32 s45, s55, 5
	s_lshl_b32 s4, s1, s45
	s_lshl_b32 s5, s5, 7
	s_add_u32 s4, s4, s5
	s_add_u32 s88, s8, s4
	s_addc_u32 s89, s9, 0
	s_add_u32 s45, s43, 2
	v_lshlrev_b32_e32 v194, s45, v200
	v_add_u32_e32 v194, v194, v201
	s_lshl_b32 s4, 1, s43
	v_add_u32_e32 v195, s4, v194
	v_add_u32_e32 v196, s4, v195
	v_add_u32_e32 v197, s4, v196
	global_load_dwordx4 v[0:3], v194, s[80:81]
	global_load_dwordx4 v[4:7], v195, s[80:81]
	global_load_dwordx4 v[8:11], v196, s[80:81]
	global_load_dwordx4 v[12:15], v197, s[80:81]
	global_load_dwordx4 v[16:19], v194, s[82:83]
	global_load_dwordx4 v[20:23], v195, s[82:83]
	global_load_dwordx4 v[24:27], v196, s[82:83]
	global_load_dwordx4 v[28:31], v197, s[82:83]
	global_load_dwordx4 v[32:35], v194, s[84:85]
	global_load_dwordx4 v[36:39], v195, s[84:85]
	global_load_dwordx4 v[40:43], v196, s[84:85]
	global_load_dwordx4 v[44:47], v197, s[84:85]
	global_load_dwordx4 v[48:51], v194, s[86:87]
	global_load_dwordx4 v[52:55], v195, s[86:87]
	global_load_dwordx4 v[56:59], v196, s[86:87]
	global_load_dwordx4 v[60:63], v197, s[86:87]
	s_waitcnt vmcnt(40)
	v_pk_mul_f32 v[64:65], v[64:65], s[40:41]
	v_pk_mul_f32 v[66:67], v[66:67], s[40:41]
	v_pk_mul_f32 v[68:69], v[68:69], s[40:41]
	v_pk_mul_f32 v[70:71], v[70:71], s[40:41]
	v_pk_mul_f32 v[72:73], v[72:73], s[40:41]
	v_pk_mul_f32 v[74:75], v[74:75], s[40:41]
	v_pk_mul_f32 v[76:77], v[76:77], s[40:41]
	v_pk_mul_f32 v[78:79], v[78:79], s[40:41]
	v_pk_mul_f32 v[80:81], v[80:81], s[40:41]
	v_pk_mul_f32 v[82:83], v[82:83], s[40:41]
	v_pk_mul_f32 v[84:85], v[84:85], s[40:41]
	v_pk_mul_f32 v[86:87], v[86:87], s[40:41]
	v_pk_mul_f32 v[88:89], v[88:89], s[40:41]
	v_pk_mul_f32 v[90:91], v[90:91], s[40:41]
	v_pk_mul_f32 v[92:93], v[92:93], s[40:41]
	v_pk_mul_f32 v[94:95], v[94:95], s[40:41]
	v_pk_mul_f32 v[96:97], v[96:97], s[40:41]
	v_pk_mul_f32 v[98:99], v[98:99], s[40:41]
	v_pk_mul_f32 v[100:101], v[100:101], s[40:41]
	v_pk_mul_f32 v[102:103], v[102:103], s[40:41]
	v_pk_mul_f32 v[104:105], v[104:105], s[40:41]
	v_pk_mul_f32 v[106:107], v[106:107], s[40:41]
	v_pk_mul_f32 v[108:109], v[108:109], s[40:41]
	v_pk_mul_f32 v[110:111], v[110:111], s[40:41]
	v_pk_mul_f32 v[112:113], v[112:113], s[40:41]
	v_pk_mul_f32 v[114:115], v[114:115], s[40:41]
	v_pk_mul_f32 v[116:117], v[116:117], s[40:41]
	v_pk_mul_f32 v[118:119], v[118:119], s[40:41]
	v_pk_mul_f32 v[120:121], v[120:121], s[40:41]
	v_pk_mul_f32 v[122:123], v[122:123], s[40:41]
	v_pk_mul_f32 v[124:125], v[124:125], s[40:41]
	v_pk_mul_f32 v[126:127], v[126:127], s[40:41]
	v_cvt_pk_fp8_f32 v64, v64, v68
	v_cvt_pk_fp8_f32 v65, v65, v69
	v_cvt_pk_fp8_f32 v66, v66, v70
	v_cvt_pk_fp8_f32 v67, v67, v71
	v_cvt_pk_fp8_f32 v64, v72, v76 op_sel:[0,0,1]
	v_cvt_pk_fp8_f32 v65, v73, v77 op_sel:[0,0,1]
	v_cvt_pk_fp8_f32 v66, v74, v78 op_sel:[0,0,1]
	v_cvt_pk_fp8_f32 v67, v75, v79 op_sel:[0,0,1]
	v_cvt_pk_fp8_f32 v80, v80, v84
	v_cvt_pk_fp8_f32 v81, v81, v85
	v_cvt_pk_fp8_f32 v82, v82, v86
	v_cvt_pk_fp8_f32 v83, v83, v87
	v_cvt_pk_fp8_f32 v80, v88, v92 op_sel:[0,0,1]
	v_cvt_pk_fp8_f32 v81, v89, v93 op_sel:[0,0,1]
	v_cvt_pk_fp8_f32 v82, v90, v94 op_sel:[0,0,1]
	v_cvt_pk_fp8_f32 v83, v91, v95 op_sel:[0,0,1]
	v_cvt_pk_fp8_f32 v96, v96, v100
	v_cvt_pk_fp8_f32 v97, v97, v101
	v_cvt_pk_fp8_f32 v98, v98, v102
	v_cvt_pk_fp8_f32 v99, v99, v103
	v_cvt_pk_fp8_f32 v96, v104, v108 op_sel:[0,0,1]
	v_cvt_pk_fp8_f32 v97, v105, v109 op_sel:[0,0,1]
	v_cvt_pk_fp8_f32 v98, v106, v110 op_sel:[0,0,1]
	v_cvt_pk_fp8_f32 v99, v107, v111 op_sel:[0,0,1]
	v_cvt_pk_fp8_f32 v112, v112, v116
	v_cvt_pk_fp8_f32 v113, v113, v117
	v_cvt_pk_fp8_f32 v114, v114, v118
	v_cvt_pk_fp8_f32 v115, v115, v119
	v_cvt_pk_fp8_f32 v112, v120, v124 op_sel:[0,0,1]
	v_cvt_pk_fp8_f32 v113, v121, v125 op_sel:[0,0,1]
	v_cvt_pk_fp8_f32 v114, v122, v126 op_sel:[0,0,1]
	v_cvt_pk_fp8_f32 v115, v123, v127 op_sel:[0,0,1]
	s_nop 0
	ds_write2_b32 v198, v64, v80 offset0:0 offset1:8
	ds_write2_b32 v198, v96, v112 offset0:16 offset1:24
	ds_write2_b32 v198, v65, v81 offset0:36 offset1:44
	ds_write2_b32 v198, v97, v113 offset0:52 offset1:60
	ds_write2_b32 v198, v66, v82 offset0:72 offset1:80
	ds_write2_b32 v198, v98, v114 offset0:88 offset1:96
	ds_write2_b32 v198, v67, v83 offset0:108 offset1:116
	ds_write2_b32 v198, v99, v115 offset0:124 offset1:132
	v_lshlrev_b32_e32 v72, s58, v200
	v_add_u32_e32 v72, v72, v201
	s_add_u32 s45, s58, 3
	s_lshl_b32 s4, 1, s45
	v_add_u32_e32 v88, s4, v72
	v_add_u32_e32 v104, s4, v88
	v_add_u32_e32 v120, s4, v104
	s_waitcnt lgkmcnt(0)
	ds_read_b128 v[68:71], v199 offset:0
	ds_read_b128 v[84:87], v199 offset:1152
	ds_read_b128 v[100:103], v199 offset:2304
	ds_read_b128 v[116:119], v199 offset:3456
	s_waitcnt lgkmcnt(3)
	global_store_dwordx4 v72, v[68:71], s[90:91]
	s_waitcnt lgkmcnt(2)
	global_store_dwordx4 v88, v[84:87], s[90:91]
	s_waitcnt lgkmcnt(1)
	global_store_dwordx4 v104, v[100:103], s[90:91]
	s_waitcnt lgkmcnt(0)
	global_store_dwordx4 v120, v[116:119], s[90:91]
	s_min_u32 s5, s3, 9215
	s_add_u32 s3, s3, 384
	s_cmp_lt_u32 s5, 0x400
	s_cbranch_scc1 .Lcp_m0_7
	s_cmp_lt_u32 s5, 0x1400
	s_cbranch_scc1 .Lcp_m1_7
	s_sub_u32 s5, s5, 0x1400
	s_and_b32 s1, s5, 63
	s_lshr_b32 s5, s5, 6
	s_mov_b32 s43, 13
	s_mov_b32 s58, 13
	s_mov_b64 s[6:7], s[98:99]
	s_add_u32 s8, s28, 0x4500000
	s_addc_u32 s9, s29, 0
	s_branch .Lcp_md_7

.Lcp_md_7:
	s_add_u32 s45, s43, 7
	s_lshl_b32 s53, s5, s45
	s_lshl_b32 s4, s1, 7
	s_add_u32 s53, s53, s4
	s_add_u32 s80, s6, s53
	s_addc_u32 s81, s7, 0
	s_add_u32 s45, s43, 5
	s_lshl_b32 s4, 1, s45
	s_add_u32 s82, s80, s4
	s_addc_u32 s83, s81, 0
	s_add_u32 s84, s82, s4
	s_addc_u32 s85, s83, 0
	s_add_u32 s86, s84, s4
	s_addc_u32 s87, s85, 0
	s_add_u32 s45, s58, 5
	s_lshl_b32 s4, s1, s45
	s_lshl_b32 s5, s5, 7
	s_add_u32 s4, s4, s5
	s_add_u32 s90, s8, s4
	s_addc_u32 s91, s9, 0
	s_add_u32 s45, s43, 2
	v_lshlrev_b32_e32 v194, s45, v200
	v_add_u32_e32 v194, v194, v201
	s_lshl_b32 s4, 1, s43
	v_add_u32_e32 v195, s4, v194
	v_add_u32_e32 v196, s4, v195
	v_add_u32_e32 v197, s4, v196
	global_load_dwordx4 v[64:67], v194, s[80:81]
	global_load_dwordx4 v[68:71], v195, s[80:81]
	global_load_dwordx4 v[72:75], v196, s[80:81]
	global_load_dwordx4 v[76:79], v197, s[80:81]
	global_load_dwordx4 v[80:83], v194, s[82:83]
	global_load_dwordx4 v[84:87], v195, s[82:83]
	global_load_dwordx4 v[88:91], v196, s[82:83]
	global_load_dwordx4 v[92:95], v197, s[82:83]
	global_load_dwordx4 v[96:99], v194, s[84:85]
	global_load_dwordx4 v[100:103], v195, s[84:85]
	global_load_dwordx4 v[104:107], v196, s[84:85]
	global_load_dwordx4 v[108:111], v197, s[84:85]
	global_load_dwordx4 v[112:115], v194, s[86:87]
	global_load_dwordx4 v[116:119], v195, s[86:87]
	global_load_dwordx4 v[120:123], v196, s[86:87]
	global_load_dwordx4 v[124:127], v197, s[86:87]
	s_waitcnt vmcnt(40)
	v_pk_mul_f32 v[128:129], v[128:129], s[40:41]
	v_pk_mul_f32 v[130:131], v[130:131], s[40:41]
	v_pk_mul_f32 v[132:133], v[132:133], s[40:41]
	v_pk_mul_f32 v[134:135], v[134:135], s[40:41]
	v_pk_mul_f32 v[136:137], v[136:137], s[40:41]
	v_pk_mul_f32 v[138:139], v[138:139], s[40:41]
	v_pk_mul_f32 v[140:141], v[140:141], s[40:41]
	v_pk_mul_f32 v[142:143], v[142:143], s[40:41]
	v_pk_mul_f32 v[144:145], v[144:145], s[40:41]
	v_pk_mul_f32 v[146:147], v[146:147], s[40:41]
	v_pk_mul_f32 v[148:149], v[148:149], s[40:41]
	v_pk_mul_f32 v[150:151], v[150:151], s[40:41]
	v_pk_mul_f32 v[152:153], v[152:153], s[40:41]
	v_pk_mul_f32 v[154:155], v[154:155], s[40:41]
	v_pk_mul_f32 v[156:157], v[156:157], s[40:41]
	v_pk_mul_f32 v[158:159], v[158:159], s[40:41]
	v_pk_mul_f32 v[160:161], v[160:161], s[40:41]
	v_pk_mul_f32 v[162:163], v[162:163], s[40:41]
	v_pk_mul_f32 v[164:165], v[164:165], s[40:41]
	v_pk_mul_f32 v[166:167], v[166:167], s[40:41]
	v_pk_mul_f32 v[168:169], v[168:169], s[40:41]
	v_pk_mul_f32 v[170:171], v[170:171], s[40:41]
	v_pk_mul_f32 v[172:173], v[172:173], s[40:41]
	v_pk_mul_f32 v[174:175], v[174:175], s[40:41]
	v_pk_mul_f32 v[176:177], v[176:177], s[40:41]
	v_pk_mul_f32 v[178:179], v[178:179], s[40:41]
	v_pk_mul_f32 v[180:181], v[180:181], s[40:41]
	v_pk_mul_f32 v[182:183], v[182:183], s[40:41]
	v_pk_mul_f32 v[186:187], v[186:187], s[40:41]
	v_pk_mul_f32 v[188:189], v[188:189], s[40:41]
	v_pk_mul_f32 v[190:191], v[190:191], s[40:41]
	v_pk_mul_f32 v[192:193], v[192:193], s[40:41]
	v_cvt_pk_fp8_f32 v128, v128, v132
	v_cvt_pk_fp8_f32 v129, v129, v133
	v_cvt_pk_fp8_f32 v130, v130, v134
	v_cvt_pk_fp8_f32 v131, v131, v135
	v_cvt_pk_fp8_f32 v128, v136, v140 op_sel:[0,0,1]
	v_cvt_pk_fp8_f32 v129, v137, v141 op_sel:[0,0,1]
	v_cvt_pk_fp8_f32 v130, v138, v142 op_sel:[0,0,1]
	v_cvt_pk_fp8_f32 v131, v139, v143 op_sel:[0,0,1]
	v_cvt_pk_fp8_f32 v144, v144, v148
	v_cvt_pk_fp8_f32 v145, v145, v149
	v_cvt_pk_fp8_f32 v146, v146, v150
	v_cvt_pk_fp8_f32 v147, v147, v151
	v_cvt_pk_fp8_f32 v144, v152, v156 op_sel:[0,0,1]
	v_cvt_pk_fp8_f32 v145, v153, v157 op_sel:[0,0,1]
	v_cvt_pk_fp8_f32 v146, v154, v158 op_sel:[0,0,1]
	v_cvt_pk_fp8_f32 v147, v155, v159 op_sel:[0,0,1]
	v_cvt_pk_fp8_f32 v160, v160, v164
	v_cvt_pk_fp8_f32 v161, v161, v165
	v_cvt_pk_fp8_f32 v162, v162, v166
	v_cvt_pk_fp8_f32 v163, v163, v167
	v_cvt_pk_fp8_f32 v160, v168, v172 op_sel:[0,0,1]
	v_cvt_pk_fp8_f32 v161, v169, v173 op_sel:[0,0,1]
	v_cvt_pk_fp8_f32 v162, v170, v174 op_sel:[0,0,1]
	v_cvt_pk_fp8_f32 v163, v171, v175 op_sel:[0,0,1]
	v_cvt_pk_fp8_f32 v176, v176, v180
	v_cvt_pk_fp8_f32 v177, v177, v181
	v_cvt_pk_fp8_f32 v178, v178, v182
	v_cvt_pk_fp8_f32 v179, v179, v183
	v_cvt_pk_fp8_f32 v176, v186, v190 op_sel:[0,0,1]
	v_cvt_pk_fp8_f32 v177, v187, v191 op_sel:[0,0,1]
	v_cvt_pk_fp8_f32 v178, v188, v192 op_sel:[0,0,1]
	v_cvt_pk_fp8_f32 v179, v189, v193 op_sel:[0,0,1]
	s_nop 0
	ds_write2_b32 v198, v128, v144 offset0:0 offset1:8
	ds_write2_b32 v198, v160, v176 offset0:16 offset1:24
	ds_write2_b32 v198, v129, v145 offset0:36 offset1:44
	ds_write2_b32 v198, v161, v177 offset0:52 offset1:60
	ds_write2_b32 v198, v130, v146 offset0:72 offset1:80
	ds_write2_b32 v198, v162, v178 offset0:88 offset1:96
	ds_write2_b32 v198, v131, v147 offset0:108 offset1:116
	ds_write2_b32 v198, v163, v179 offset0:124 offset1:132
	v_lshlrev_b32_e32 v136, s59, v200
	v_add_u32_e32 v136, v136, v201
	s_add_u32 s45, s59, 3
	s_lshl_b32 s4, 1, s45
	v_add_u32_e32 v152, s4, v136
	v_add_u32_e32 v168, s4, v152
	v_add_u32_e32 v186, s4, v168
	s_waitcnt lgkmcnt(0)
	ds_read_b128 v[132:135], v199 offset:0
	ds_read_b128 v[148:151], v199 offset:1152
	ds_read_b128 v[164:167], v199 offset:2304
	ds_read_b128 v[180:183], v199 offset:3456
	s_waitcnt lgkmcnt(3)
	global_store_dwordx4 v136, v[132:135], s[92:93]
	s_waitcnt lgkmcnt(2)
	global_store_dwordx4 v152, v[148:151], s[92:93]
	s_waitcnt lgkmcnt(1)
	global_store_dwordx4 v168, v[164:167], s[92:93]
	s_waitcnt lgkmcnt(0)
	global_store_dwordx4 v186, v[180:183], s[92:93]
	s_add_u32 s18, s18, 3
	s_cmp_lt_u32 s18, 24
	s_cbranch_scc1 .Lcp_loop
	s_waitcnt vmcnt(0)
	v_mov_b32_e32 v108, v184
	v_and_b32_e32 v146, 63, v108
	s_branch .Lscan_setup

.LBB0_1325:
	s_endpgm
	.section	.rodata,"a",@progbits
	.p2align	6, 0x0
	.amdhsa_kernel _Z10fwd_kernel4Args
		.amdhsa_group_segment_fixed_size 0
		.amdhsa_private_segment_fixed_size 0
		.amdhsa_kernarg_size 488
		.amdhsa_user_sgpr_count 2
		.amdhsa_user_sgpr_dispatch_ptr 0
		.amdhsa_user_sgpr_queue_ptr 0
		.amdhsa_user_sgpr_kernarg_segment_ptr 1
		.amdhsa_user_sgpr_dispatch_id 0
		.amdhsa_user_sgpr_kernarg_preload_length 0
		.amdhsa_user_sgpr_kernarg_preload_offset 0
		.amdhsa_user_sgpr_private_segment_size 0
		.amdhsa_uses_dynamic_stack 0
		.amdhsa_enable_private_segment 0
		.amdhsa_system_sgpr_workgroup_id_x 1
		.amdhsa_system_sgpr_workgroup_id_y 0
		.amdhsa_system_sgpr_workgroup_id_z 0
		.amdhsa_system_sgpr_workgroup_info 0
		.amdhsa_system_vgpr_workitem_id 2
		.amdhsa_next_free_vgpr 255
		.amdhsa_next_free_sgpr 102
		.amdhsa_accum_offset 256
		.amdhsa_reserve_vcc 1
		.amdhsa_float_round_mode_32 0
		.amdhsa_float_round_mode_16_64 0
		.amdhsa_float_denorm_mode_32 3
		.amdhsa_float_denorm_mode_16_64 3
		.amdhsa_dx10_clamp 1
		.amdhsa_ieee_mode 1
		.amdhsa_fp16_overflow 0
		.amdhsa_tg_split 0
		.amdhsa_exception_fp_ieee_invalid_op 0
		.amdhsa_exception_fp_denorm_src 0
		.amdhsa_exception_fp_ieee_div_zero 0
		.amdhsa_exception_fp_ieee_overflow 0
		.amdhsa_exception_fp_ieee_underflow 0
		.amdhsa_exception_fp_ieee_inexact 0
		.amdhsa_exception_int_div_zero 0
	.end_amdhsa_kernel

amdhsa.kernels:
  - .agpr_count:     0
    .args:
      - .offset:         0
        .size:           232
        .value_kind:     by_value
      - .offset:         232
        .size:           4
        .value_kind:     hidden_block_count_x
      - .offset:         236
        .size:           4
        .value_kind:     hidden_block_count_y
      - .offset:         240
        .size:           4
        .value_kind:     hidden_block_count_z
      - .offset:         244
        .size:           2
        .value_kind:     hidden_group_size_x
      - .offset:         246
        .size:           2
        .value_kind:     hidden_group_size_y
      - .offset:         248
        .size:           2
        .value_kind:     hidden_group_size_z
      - .offset:         250
        .size:           2
        .value_kind:     hidden_remainder_x
      - .offset:         252
        .size:           2
        .value_kind:     hidden_remainder_y
      - .offset:         254
        .size:           2
        .value_kind:     hidden_remainder_z
      - .offset:         272
        .size:           8
        .value_kind:     hidden_global_offset_x
      - .offset:         280
        .size:           8
        .value_kind:     hidden_global_offset_y
      - .offset:         288
        .size:           8
        .value_kind:     hidden_global_offset_z
      - .offset:         296
        .size:           2
        .value_kind:     hidden_grid_dims
      - .offset:         320
        .size:           8
        .value_kind:     hidden_multigrid_sync_arg
      - .offset:         352
        .size:           4
        .value_kind:     hidden_dynamic_lds_size
    .group_segment_fixed_size: 0
    .kernarg_segment_align: 8
    .kernarg_segment_size: 488
    .language:       OpenCL C
    .language_version:
      - 2
      - 0
    .max_flat_workgroup_size: 512
    .name:           _Z10fwd_kernel4Args
    .private_segment_fixed_size: 0
    .sgpr_count:     108
    .sgpr_spill_count: 65
    .symbol:         _Z10fwd_kernel4Args.kd
    .uniform_work_group_size: 1
    .uses_dynamic_stack: false
    .vgpr_count:     255
    .vgpr_spill_count: 0
    .wavefront_size: 64
